# kv-up unit assignment rotated so q-up + kv-up units per workgroup max 4 instead of 5
# baseline (speedup 1.0000x reference)
.LBB0_462:
	s_and_b64 s[0:1], s[6:7], exec
	s_movk_i32 s0, 0x600
	s_cselect_b32 s15, s0, 0x800
	s_cselect_b32 s49, s14, 0x44
	s_cselect_b32 s100, 0, 1
	s_mul_i32 s101, s14, 6
	s_sub_i32 s101, s2, s101
	s_and_b32 s101, s101, 0xff
	s_cmp_eq_u32 s34, 0x100
	s_cselect_b32 s101, s101, s2
	s_cmp_eq_u32 s100, 0
	s_cselect_b32 s100, s2, s101
	s_lshr_b32 s50, s15, 8
	s_mul_i32 s50, s50, s49
	s_mov_b32 s0, s3
	v_mbcnt_lo_u32_b32 v8, -1, 0
	v_mbcnt_hi_u32_b32 v8, -1, v8
	s_cmp_lt_i32 s100, s50
	v_lshl_add_u32 v0, s0, 6, v8
	s_cselect_b64 s[0:1], -1, 0
	s_cmp_ge_i32 s100, s50
	v_readfirstlane_b32 s12, v0
	s_cbranch_scc1 .LBB0_461
	s_and_b64 s[8:9], s[6:7], exec
	s_cselect_b32 s8, 0, 0x400
	s_add_u32 s51, s42, s8
	s_addc_u32 s58, s43, 0
	s_and_b64 s[8:9], s[6:7], exec
	s_mov_b32 s8, 0xc00000
	s_cselect_b32 s8, s8, 0xd80000
	v_readlane_b32 s9, v246, 52
	s_add_u32 s59, s9, s8
	v_readlane_b32 s8, v246, 53
	s_addc_u32 s60, s8, 0
	s_ashr_i32 s13, s12, 6
	s_ashr_i32 s16, s12, 8
	s_lshl_b32 s61, s13, 10
	s_and_b64 s[0:1], s[0:1], exec
	s_cselect_b32 s0, s100, 0
	s_ashr_i32 s1, s0, 31
	s_lshr_b32 s1, s1, 29
	s_add_i32 s1, s0, s1
	s_lshr_b32 s62, s50, 3
	s_ashr_i32 s8, s1, 3
	s_and_b32 s1, s1, -8
	s_sub_i32 s0, s0, s1
	s_add_i32 s63, s62, 1
	s_cmp_lt_i32 s0, 0
	s_cselect_b32 s1, s63, s62
	s_lshr_b32 s66, s15, 5
	v_cvt_f32_ubyte0_e32 v1, s66
	v_rcp_iflag_f32_e32 v1, v1
	s_sub_i32 s9, 0, s66
	s_mul_i32 s0, s1, s0
	s_add_i32 s0, s0, s8
	v_mul_f32_e32 v1, 0x4f7ffffe, v1
	v_cvt_u32_f32_e32 v1, v1
	s_abs_i32 s8, s0
	s_ashr_i32 s1, s0, 31
	v_mov_b32_e32 v129, v161
	v_readfirstlane_b32 s67, v1
	s_mul_i32 s9, s9, s67
	s_mul_hi_u32 s9, s67, s9
	s_add_i32 s67, s67, s9
	s_mul_hi_u32 s9, s8, s67
	s_mul_i32 s10, s9, s66
	s_sub_i32 s8, s8, s10
	s_add_i32 s10, s9, 1
	s_sub_i32 s11, s8, s66
	s_cmp_ge_u32 s8, s66
	s_cselect_b32 s9, s10, s9
	s_cselect_b32 s8, s11, s8
	s_add_i32 s10, s9, 1
	s_cmp_ge_u32 s8, s66
	s_cselect_b32 s8, s10, s9
	s_xor_b32 s8, s8, s1
	s_sub_i32 s1, s8, s1
	s_lshl_b32 s8, s1, 3
	s_sub_i32 s9, s49, s8
	s_min_i32 s9, s9, 8
	s_abs_i32 s10, s9
	v_cvt_f32_u32_e32 v1, s10
	s_sub_i32 s17, 0, s10
	s_mul_i32 s1, s1, s66
	s_sub_i32 s0, s0, s1
	v_rcp_iflag_f32_e32 v1, v1
	s_abs_i32 s11, s0
	s_xor_b32 s1, s0, s9
	s_ashr_i32 s1, s1, 31
	v_mul_f32_e32 v1, 0x4f7ffffe, v1
	v_cvt_u32_f32_e32 v1, v1
	v_mov_b32_e32 v133, v161
	v_mov_b32_e32 v131, v161
	v_readfirstlane_b32 s18, v1
	s_mul_i32 s17, s17, s18
	v_lshlrev_b32_e32 v1, 4, v0
	s_mul_hi_u32 s17, s18, s17
	v_add_u32_e32 v2, 0x2000, v1
	s_add_i32 s18, s18, s17
	v_ashrrev_i32_e32 v3, 31, v2
	s_mul_hi_u32 s17, s11, s18
	v_lshrrev_b32_e32 v3, 22, v3
	s_mul_i32 s18, s17, s10
	v_add_u32_e32 v3, v2, v3
	s_sub_i32 s11, s11, s18
	v_ashrrev_i32_e32 v9, 10, v3
	s_add_i32 s18, s17, 1
	s_sub_i32 s19, s11, s10
	v_mul_i32_i24_e32 v3, 0x400, v9
	s_cmp_ge_u32 s11, s10
	v_sub_u32_e32 v2, v2, v3
	s_cselect_b32 s17, s18, s17
	v_lshrrev_b32_e32 v3, 4, v2
	s_cselect_b32 s11, s19, s11
	s_add_i32 s18, s17, 1
	v_bitop3_b32 v2, v3, v2, 32 bitop3:0x6c
	s_cmp_ge_u32 s11, s10
	v_ashrrev_i32_e32 v3, 31, v2
	s_cselect_b32 s10, s18, s17
	v_lshrrev_b32_e32 v3, 26, v3
	s_xor_b32 s10, s10, s1
	v_add_u32_e32 v3, v2, v3
	v_lshlrev_b32_e32 v4, 3, v9
	s_sub_i32 s30, s10, s1
	v_ashrrev_i32_e32 v10, 6, v3
	v_and_b32_e32 v4, -16, v4
	s_mul_i32 s1, s30, s9
	v_add_u32_e32 v4, v10, v4
	s_sub_i32 s0, s0, s1
	v_and_b32_e32 v5, 3, v10
	s_mov_b32 s1, 0x3fffe0
	v_lshrrev_b32_e32 v6, 2, v4
	v_lshlrev_b32_e32 v7, 1, v4
	v_and_b32_e32 v3, 0xc0, v3
	v_and_or_b32 v5, v4, s1, v5
	v_and_b32_e32 v6, 4, v6
	v_and_b32_e32 v7, 24, v7
	v_sub_u32_e32 v2, v2, v3
	v_or3_b32 v5, v5, v6, v7
	v_lshlrev_b32_e32 v6, 5, v9
	v_ashrrev_i16_sdwa v2, v177, sext(v2) dst_sel:DWORD dst_unused:UNUSED_PAD src0_sel:DWORD src1_sel:BYTE_0
	v_and_b32_e32 v11, 32, v6
	v_bfe_i32 v12, v2, 0, 16
	v_add_u32_e32 v2, v11, v12
	v_lshlrev_b32_e32 v3, 1, v2
	v_lshl_add_u32 v128, v5, 10, v3
	v_mul_lo_u32 v3, v4, s38
	v_add_lshl_u32 v130, v2, v3, 1
	v_bfe_i32 v2, v0, 27, 1
	v_lshrrev_b32_e32 v2, 22, v2
	v_add_u32_e32 v2, v1, v2
	v_and_b32_e32 v2, 0xfffffc00, v2
	v_sub_u32_e32 v1, v1, v2
	v_lshrrev_b32_e32 v2, 4, v1
	v_ashrrev_i32_e32 v3, 31, v0
	v_bitop3_b32 v1, v2, v1, 32 bitop3:0x6c
	v_lshrrev_b32_e32 v3, 26, v3
	v_ashrrev_i32_e32 v2, 31, v1
	v_add_u32_e32 v0, v0, v3
	v_lshrrev_b32_e32 v2, 26, v2
	v_ashrrev_i32_e32 v14, 6, v0
	v_add_u32_e32 v2, v1, v2
	v_lshlrev_b32_e32 v0, 3, v14
	v_ashrrev_i32_e32 v13, 6, v2
	v_and_b32_e32 v0, -16, v0
	v_add_u32_e32 v0, v13, v0
	v_and_b32_e32 v3, 3, v13
	v_lshrrev_b32_e32 v4, 2, v0
	v_lshlrev_b32_e32 v5, 1, v0
	v_and_b32_e32 v2, 0xc0, v2
	v_and_or_b32 v3, v0, s1, v3
	v_and_b32_e32 v4, 4, v4
	v_and_b32_e32 v5, 24, v5
	v_sub_u32_e32 v1, v1, v2
	v_or3_b32 v3, v3, v4, v5
	v_lshlrev_b32_e32 v4, 5, v14
	v_ashrrev_i16_sdwa v1, v177, sext(v1) dst_sel:DWORD dst_unused:UNUSED_PAD src0_sel:DWORD src1_sel:BYTE_0
	s_ashr_i32 s31, s30, 31
	s_add_i32 s0, s0, s8
	v_and_b32_e32 v15, 32, v4
	v_bfe_i32 v16, v1, 0, 16
	s_lshl_b64 s[8:9], s[30:31], 18
	v_add_u32_e32 v1, v15, v16
	s_add_u32 s18, s59, s8
	v_lshlrev_b32_e32 v2, 1, v1
	s_addc_u32 s19, s60, s9
	s_add_i32 s31, s61, 0
	v_lshl_add_u32 v160, v3, 10, v2
	s_add_i32 m0, s31, 0x10000
	s_mul_i32 s10, s0, 0x180000
	global_load_lds_dwordx4 v160, s[18:19]
	s_add_i32 m0, s31, 0x12000
	s_add_u32 s8, s18, 0x20000
	global_load_lds_dwordx4 v128, s[18:19]
	s_addc_u32 s9, s19, 0
	s_add_i32 m0, s31, 0x14000
	s_mul_hi_i32 s1, s0, 0x180000
	global_load_lds_dwordx4 v160, s[8:9]
	s_add_i32 m0, s31, 0x16000
	s_add_u32 s72, s51, s10
	v_mul_lo_u32 v0, v0, s38
	s_addc_u32 s73, s58, s1
	s_add_i32 s68, s31, 0x2000
	v_add_lshl_u32 v132, v1, v0, 1
	global_load_lds_dwordx4 v128, s[8:9]
	s_mov_b32 m0, s31
	s_add_u32 s8, s72, 0xc0000
	global_load_lds_dwordx4 v132, s[72:73]
	s_mov_b32 m0, s68
	s_addc_u32 s9, s73, 0
	s_add_i32 s74, s31, 0x4000
	global_load_lds_dwordx4 v130, s[72:73]
	s_mov_b32 m0, s74
	s_add_i32 s75, s31, 0x6000
	global_load_lds_dwordx4 v132, s[8:9]
	s_mov_b32 m0, s75
	s_cmp_eq_u32 s16, 1
	global_load_lds_dwordx4 v130, s[8:9]
	v_lshl_add_u64 v[6:7], s[18:19], 0, v[160:161]
	v_lshl_add_u64 v[4:5], s[18:19], 0, v[128:129]
	v_lshl_add_u64 v[0:1], s[72:73], 0, v[132:133]
	s_cselect_b64 s[8:9], -1, 0
	s_cmp_lg_u32 s16, 1
	v_lshl_add_u64 v[2:3], s[72:73], 0, v[130:131]
	s_cbranch_scc1 .LBB0_465
	s_barrier

.LBB0_468:
	s_add_i32 s78, s78, 1
	s_mul_i32 s1, s78, s34
	s_add_i32 s1, s1, s100
	s_cmp_lt_i32 s1, s50
	s_cselect_b64 s[22:23], -1, 0
	s_and_b64 s[20:21], s[22:23], exec
	s_cselect_b32 s20, s1, 0
	s_ashr_i32 s21, s20, 31
	s_lshr_b32 s21, s21, 29
	s_add_i32 s21, s20, s21
	s_ashr_i32 s44, s21, 3
	s_and_b32 s21, s21, -8
	s_sub_i32 s20, s20, s21
	s_cmp_lt_i32 s20, 0
	s_cselect_b32 s21, s63, s62
	s_mul_i32 s20, s21, s20
	s_add_i32 s20, s20, s44
	s_abs_i32 s44, s20
	s_mul_hi_u32 s45, s44, s67
	s_mul_i32 s54, s45, s66
	s_sub_i32 s44, s44, s54
	s_ashr_i32 s21, s20, 31
	s_add_i32 s54, s45, 1
	s_sub_i32 s55, s44, s66
	s_cmp_ge_u32 s44, s66
	s_cselect_b32 s45, s54, s45
	s_cselect_b32 s44, s55, s44
	s_add_i32 s54, s45, 1
	s_cmp_ge_u32 s44, s66
	s_cselect_b32 s44, s54, s45
	s_xor_b32 s44, s44, s21
	s_sub_i32 s21, s44, s21
	s_lshl_b32 s44, s21, 3
	s_sub_i32 s45, s49, s44
	s_min_i32 s45, s45, 8
	s_abs_i32 s54, s45
	v_cvt_f32_u32_e32 v0, s54
	s_sub_i32 s70, 0, s54
	s_mul_i32 s21, s21, s66
	s_sub_i32 s20, s20, s21
	v_rcp_iflag_f32_e32 v0, v0
	s_abs_i32 s55, s20
	s_xor_b32 s21, s20, s45
	s_ashr_i32 s21, s21, 31
	v_mul_f32_e32 v0, 0x4f7ffffe, v0
	v_cvt_u32_f32_e32 v0, v0
	s_nop 0
	v_readfirstlane_b32 s71, v0
	s_mul_i32 s70, s70, s71
	s_mul_hi_u32 s70, s71, s70
	s_add_i32 s71, s71, s70
	s_mul_hi_u32 s70, s55, s71
	s_mul_i32 s71, s70, s54
	s_sub_i32 s55, s55, s71
	s_add_i32 s71, s70, 1
	s_sub_i32 s79, s55, s54
	s_cmp_ge_u32 s55, s54
	s_cselect_b32 s70, s71, s70
	s_cselect_b32 s55, s79, s55
	s_add_i32 s71, s70, 1
	s_cmp_ge_u32 s55, s54
	s_cselect_b32 s54, s71, s70
	s_xor_b32 s54, s54, s21
	s_sub_i32 s54, s54, s21
	s_mul_i32 s21, s54, s45
	s_sub_i32 s79, s20, s21
	s_add_i32 s79, s79, s44
	s_cmp_ge_i32 s1, s50
	s_cbranch_scc1 .LBB0_470
	s_mul_i32 s16, s79, 0x180000
	s_mul_hi_i32 s1, s79, 0x180000
	s_add_u32 s16, s51, s16
	s_addc_u32 s17, s58, s1
